# NSA window loop: tile row-sum as overflow detector, row-max and rescale only on rare slow path (same as selected branch)
# baseline (speedup 1.0000x reference)
.LBB0_646:
	s_nop 9
	v_fma_f32 v0, v66, s66, -v202
	v_exp_f32_e32 v203, v0
	v_fma_f32 v0, v67, s66, -v202
	v_exp_f32_e32 v204, v0
	v_fma_f32 v0, v68, s66, -v202
	v_exp_f32_e32 v205, v0
	v_fma_f32 v0, v69, s66, -v202
	v_exp_f32_e32 v206, v0
	v_fma_f32 v0, v70, s66, -v202
	v_exp_f32_e32 v207, v0
	v_fma_f32 v0, v71, s66, -v202
	v_exp_f32_e32 v208, v0
	v_fma_f32 v0, v72, s66, -v202
	v_exp_f32_e32 v209, v0
	v_fma_f32 v0, v73, s66, -v202
	v_exp_f32_e32 v210, v0
	v_fma_f32 v0, v74, s66, -v202
	v_exp_f32_e32 v211, v0
	v_fma_f32 v0, v75, s66, -v202
	v_exp_f32_e32 v212, v0
	v_fma_f32 v0, v76, s66, -v202
	v_exp_f32_e32 v213, v0
	v_fma_f32 v0, v77, s66, -v202
	v_exp_f32_e32 v214, v0
	v_fma_f32 v0, v78, s66, -v202
	v_exp_f32_e32 v215, v0
	v_fma_f32 v0, v79, s66, -v202
	v_exp_f32_e32 v216, v0
	v_fma_f32 v0, v80, s66, -v202
	v_exp_f32_e32 v217, v0
	v_fma_f32 v0, v81, s66, -v202
	v_exp_f32_e32 v218, v0
	v_add_f32_e32 v196, v203, v204
	v_add_f32_e32 v196, v205, v196
	v_add_f32_e32 v196, v206, v196
	v_add_f32_e32 v196, v207, v196
	v_add_f32_e32 v196, v208, v196
	v_add_f32_e32 v196, v209, v196
	v_add_f32_e32 v196, v210, v196
	v_add_f32_e32 v196, v211, v196
	v_add_f32_e32 v196, v212, v196
	v_add_f32_e32 v196, v213, v196
	v_add_f32_e32 v196, v214, v196
	v_add_f32_e32 v196, v215, v196
	v_add_f32_e32 v196, v216, v196
	v_add_f32_e32 v196, v217, v196
	v_add_f32_e32 v196, v218, v196
	v_cmp_lt_f32_e32 vcc, 0x43800000, v196
	s_cbranch_vccnz .Lwin_slow0
.Lwin_join0:
	v_add_f32_e32 v147, v147, v196
	v_cvt_pk_bf16_f32 v66, v203, v204
	v_cvt_pk_bf16_f32 v67, v205, v206
	v_cvt_pk_bf16_f32 v68, v207, v208
	v_cvt_pk_bf16_f32 v69, v209, v210
	v_cvt_pk_bf16_f32 v70, v211, v212
	v_cvt_pk_bf16_f32 v71, v213, v214
	v_cvt_pk_bf16_f32 v72, v215, v216
	v_cvt_pk_bf16_f32 v73, v217, v218
	s_waitcnt vmcnt(0)
	v_mfma_f32_32x32x16_bf16 v[50:65], v[142:145], v[66:69], v[50:65]
	s_xor_b64 s[4:5], s[6:7], -1
	s_add_i32 s9, s8, 32
	s_cmp_gt_i32 s9, s10
	s_cselect_b64 s[6:7], -1, 0
	s_and_b64 s[12:13], s[6:7], exec
	v_mfma_f32_32x32x16_bf16 v[34:49], v[134:137], v[66:69], v[34:49]
	s_cselect_b32 s8, s8, s9
	v_mad_i64_i32 v[218:219], s[12:13], s8, v247, v[148:149]
	s_andn2_b64 vcc, exec, s[4:5]
	v_mfma_f32_32x32x16_bf16 v[50:65], v[138:141], v[70:73], v[50:65]
	v_mfma_f32_32x32x16_bf16 v[34:49], v[130:133], v[70:73], v[34:49]
	v_mfma_f32_32x32x16_bf16 v[66:81], v[126:129], v[98:101], 0
	v_mfma_f32_32x32x16_bf16 v[66:81], v[122:125], v[102:105], v[66:81]
	v_mfma_f32_32x32x16_bf16 v[66:81], v[118:121], v[106:109], v[66:81]
	v_mfma_f32_32x32x16_bf16 v[66:81], v[114:117], v[110:113], v[66:81]
	global_load_dwordx4 v[126:129], v[218:219], off offset:2048
	global_load_dwordx4 v[122:125], v[218:219], off offset:2080
	global_load_dwordx4 v[118:121], v[218:219], off offset:2112
	global_load_dwordx4 v[114:117], v[218:219], off offset:2144
	s_cbranch_vccnz .LBB0_651
	v_cmp_le_i32_e32 vcc, v192, v174
	v_cmp_gt_i32_e64 s[4:5], v192, v175
	s_and_b64 vcc, vcc, s[4:5]
	s_nop 3
	v_cndmask_b32_e32 v66, v248, v66, vcc
	v_cmp_lt_i32_e32 vcc, v192, v174
	v_cmp_ge_i32_e64 s[4:5], v192, v175
	s_and_b64 vcc, vcc, s[4:5]
	v_cndmask_b32_e32 v67, v248, v67, vcc
	v_cmp_le_i32_e32 vcc, v201, v174
	v_cmp_gt_i32_e64 s[4:5], v201, v175
	s_and_b64 vcc, vcc, s[4:5]
	v_cndmask_b32_e32 v68, v248, v68, vcc
	v_cmp_le_i32_e32 vcc, v200, v174
	v_cmp_gt_i32_e64 s[4:5], v200, v175
	s_and_b64 vcc, vcc, s[4:5]
	v_cndmask_b32_e32 v69, v248, v69, vcc
	v_cmp_le_i32_e32 vcc, v193, v174
	v_cmp_gt_i32_e64 s[4:5], v193, v175
	s_and_b64 vcc, vcc, s[4:5]
	v_cndmask_b32_e32 v70, v248, v70, vcc
	v_cmp_le_i32_e32 vcc, v191, v174
	v_cmp_gt_i32_e64 s[4:5], v191, v175
	s_and_b64 vcc, vcc, s[4:5]
	v_cndmask_b32_e32 v71, v248, v71, vcc
	v_cmp_le_i32_e32 vcc, v190, v174
	v_cmp_gt_i32_e64 s[4:5], v190, v175
	s_and_b64 vcc, vcc, s[4:5]
	v_cndmask_b32_e32 v72, v248, v72, vcc
	v_cmp_le_i32_e32 vcc, v189, v174
	v_cmp_gt_i32_e64 s[4:5], v189, v175
	s_and_b64 vcc, vcc, s[4:5]
	v_cndmask_b32_e32 v73, v248, v73, vcc
	v_cmp_le_i32_e32 vcc, v188, v174
	v_cmp_gt_i32_e64 s[4:5], v188, v175
	s_and_b64 vcc, vcc, s[4:5]
	v_cndmask_b32_e32 v74, v248, v74, vcc
	v_cmp_le_i32_e32 vcc, v187, v174
	v_cmp_gt_i32_e64 s[4:5], v187, v175
	s_and_b64 vcc, vcc, s[4:5]
	v_cndmask_b32_e32 v75, v248, v75, vcc
	v_cmp_le_i32_e32 vcc, v186, v174
	v_cmp_gt_i32_e64 s[4:5], v186, v175
	s_and_b64 vcc, vcc, s[4:5]
	v_cndmask_b32_e32 v76, v248, v76, vcc
	v_cmp_le_i32_e32 vcc, v185, v174
	v_cmp_gt_i32_e64 s[4:5], v185, v175
	s_and_b64 vcc, vcc, s[4:5]
	v_cndmask_b32_e32 v77, v248, v77, vcc
	v_cmp_le_i32_e32 vcc, v184, v174
	v_cmp_gt_i32_e64 s[4:5], v184, v175
	s_and_b64 vcc, vcc, s[4:5]
	v_cndmask_b32_e32 v78, v248, v78, vcc
	v_cmp_le_i32_e32 vcc, v183, v174
	v_cmp_gt_i32_e64 s[4:5], v183, v175
	s_and_b64 vcc, vcc, s[4:5]
	v_cndmask_b32_e32 v79, v248, v79, vcc
	v_cmp_le_i32_e32 vcc, v182, v174
	v_cmp_gt_i32_e64 s[4:5], v182, v175
	s_and_b64 vcc, vcc, s[4:5]
	v_cndmask_b32_e32 v80, v248, v80, vcc
	v_cmp_le_i32_e32 vcc, v181, v174
	v_cmp_gt_i32_e64 s[4:5], v181, v175
	s_and_b64 vcc, vcc, s[4:5]
	v_cndmask_b32_e32 v81, v248, v81, vcc
.LBB0_651:
	s_nop 6
	v_fma_f32 v181, v66, s66, -v180
	v_exp_f32_e32 v203, v181
	v_fma_f32 v181, v67, s66, -v180
	v_exp_f32_e32 v204, v181
	v_fma_f32 v181, v68, s66, -v180
	v_exp_f32_e32 v205, v181
	v_fma_f32 v181, v69, s66, -v180
	v_exp_f32_e32 v206, v181
	v_fma_f32 v181, v70, s66, -v180
	v_exp_f32_e32 v207, v181
	v_fma_f32 v181, v71, s66, -v180
	v_exp_f32_e32 v208, v181
	v_fma_f32 v181, v72, s66, -v180
	v_exp_f32_e32 v209, v181
	v_fma_f32 v181, v73, s66, -v180
	v_exp_f32_e32 v210, v181
	v_fma_f32 v181, v74, s66, -v180
	v_exp_f32_e32 v211, v181
	v_fma_f32 v181, v75, s66, -v180
	v_exp_f32_e32 v212, v181
	v_fma_f32 v181, v76, s66, -v180
	v_exp_f32_e32 v213, v181
	v_fma_f32 v181, v77, s66, -v180
	v_exp_f32_e32 v214, v181
	v_fma_f32 v181, v78, s66, -v180
	v_exp_f32_e32 v215, v181
	v_fma_f32 v181, v79, s66, -v180
	v_exp_f32_e32 v216, v181
	v_fma_f32 v181, v80, s66, -v180
	v_exp_f32_e32 v217, v181
	v_fma_f32 v181, v81, s66, -v180
	v_exp_f32_e32 v218, v181
	v_add_f32_e32 v182, v203, v204
	v_add_f32_e32 v182, v205, v182
	v_add_f32_e32 v182, v206, v182
	v_add_f32_e32 v182, v207, v182
	v_add_f32_e32 v182, v208, v182
	v_add_f32_e32 v182, v209, v182
	v_add_f32_e32 v182, v210, v182
	v_add_f32_e32 v182, v211, v182
	v_add_f32_e32 v182, v212, v182
	v_add_f32_e32 v182, v213, v182
	v_add_f32_e32 v182, v214, v182
	v_add_f32_e32 v182, v215, v182
	v_add_f32_e32 v182, v216, v182
	v_add_f32_e32 v182, v217, v182
	v_add_f32_e32 v182, v218, v182
	v_cmp_lt_f32_e32 vcc, 0x43800000, v182
	s_cbranch_vccnz .Lwin_slow1
.Lwin_join1:
	v_add_f32_e32 v146, v146, v182
	v_cvt_pk_bf16_f32 v66, v203, v204
	v_cvt_pk_bf16_f32 v67, v205, v206
	v_cvt_pk_bf16_f32 v68, v207, v208
	v_cvt_pk_bf16_f32 v69, v209, v210
	v_cvt_pk_bf16_f32 v70, v211, v212
	v_cvt_pk_bf16_f32 v71, v213, v214
	v_cvt_pk_bf16_f32 v72, v215, v216
	v_cvt_pk_bf16_f32 v73, v217, v218
	v_mfma_f32_32x32x16_bf16 v[18:33], v[142:145], v[66:69], v[18:33]
	v_mfma_f32_32x32x16_bf16 v[2:17], v[134:137], v[66:69], v[2:17]
	v_mfma_f32_32x32x16_bf16 v[18:33], v[138:141], v[70:73], v[18:33]
	v_mfma_f32_32x32x16_bf16 v[2:17], v[130:133], v[70:73], v[2:17]
	v_lshl_add_u64 v[152:153], v[152:153], 0, s[48:49]
	s_and_b64 vcc, exec, s[6:7]
	s_cbranch_vccnz .LBB0_656
	s_mov_b32 s8, s9
	s_branch .LBB0_644
.Lwin_slow0:
	v_max_f32_e32 v0, v66, v67
	v_max3_f32 v0, v0, v68, v69
	v_max3_f32 v0, v0, v70, v71
	v_max3_f32 v0, v0, v72, v73
	v_max3_f32 v0, v0, v74, v75
	v_max3_f32 v0, v0, v76, v77
	v_max3_f32 v0, v0, v78, v79
	v_max3_f32 v0, v0, v80, v81
	v_mov_b32_e32 v196, v0
	s_nop 1
	v_permlane32_swap_b32_e32 v0, v196
	v_max_f32_e32 v0, v0, v196
	v_mul_f32_e32 v0, 0x3e38aa3b, v0
	v_max_f32_e32 v0, v202, v0
	v_sub_f32_e32 v196, v0, v202
	v_cmp_lt_f32_e32 vcc, s67, v196
	s_cbranch_vccz .Lwin_slow0_nr
	v_sub_f32_e32 v196, v202, v0
	v_exp_f32_e32 v204, v196
	s_nop 0
	v_mul_f32_e32 v147, v147, v204
	v_pk_mul_f32 v[64:65], v[64:65], v[204:205] op_sel_hi:[1,0]
	v_pk_mul_f32 v[62:63], v[62:63], v[204:205] op_sel_hi:[1,0]
	v_pk_mul_f32 v[60:61], v[60:61], v[204:205] op_sel_hi:[1,0]
	v_pk_mul_f32 v[58:59], v[58:59], v[204:205] op_sel_hi:[1,0]
	v_pk_mul_f32 v[56:57], v[56:57], v[204:205] op_sel_hi:[1,0]
	v_pk_mul_f32 v[54:55], v[54:55], v[204:205] op_sel_hi:[1,0]
	v_pk_mul_f32 v[52:53], v[52:53], v[204:205] op_sel_hi:[1,0]
	v_pk_mul_f32 v[50:51], v[50:51], v[204:205] op_sel_hi:[1,0]
	v_pk_mul_f32 v[48:49], v[48:49], v[204:205] op_sel_hi:[1,0]
	v_pk_mul_f32 v[46:47], v[46:47], v[204:205] op_sel_hi:[1,0]
	v_pk_mul_f32 v[44:45], v[44:45], v[204:205] op_sel_hi:[1,0]
	v_pk_mul_f32 v[42:43], v[42:43], v[204:205] op_sel_hi:[1,0]
	v_pk_mul_f32 v[40:41], v[40:41], v[204:205] op_sel_hi:[1,0]
	v_pk_mul_f32 v[38:39], v[38:39], v[204:205] op_sel_hi:[1,0]
	v_pk_mul_f32 v[36:37], v[36:37], v[204:205] op_sel_hi:[1,0]
	v_pk_mul_f32 v[34:35], v[34:35], v[204:205] op_sel_hi:[1,0]
	v_mov_b32_e32 v202, v0
.Lwin_slow0_nr:
	v_fma_f32 v0, v66, s66, -v202
	v_exp_f32_e32 v203, v0
	v_fma_f32 v0, v67, s66, -v202
	v_exp_f32_e32 v204, v0
	v_fma_f32 v0, v68, s66, -v202
	v_exp_f32_e32 v205, v0
	v_fma_f32 v0, v69, s66, -v202
	v_exp_f32_e32 v206, v0
	v_fma_f32 v0, v70, s66, -v202
	v_exp_f32_e32 v207, v0
	v_fma_f32 v0, v71, s66, -v202
	v_exp_f32_e32 v208, v0
	v_fma_f32 v0, v72, s66, -v202
	v_exp_f32_e32 v209, v0
	v_fma_f32 v0, v73, s66, -v202
	v_exp_f32_e32 v210, v0
	v_fma_f32 v0, v74, s66, -v202
	v_exp_f32_e32 v211, v0
	v_fma_f32 v0, v75, s66, -v202
	v_exp_f32_e32 v212, v0
	v_fma_f32 v0, v76, s66, -v202
	v_exp_f32_e32 v213, v0
	v_fma_f32 v0, v77, s66, -v202
	v_exp_f32_e32 v214, v0
	v_fma_f32 v0, v78, s66, -v202
	v_exp_f32_e32 v215, v0
	v_fma_f32 v0, v79, s66, -v202
	v_exp_f32_e32 v216, v0
	v_fma_f32 v0, v80, s66, -v202
	v_exp_f32_e32 v217, v0
	v_fma_f32 v0, v81, s66, -v202
	v_exp_f32_e32 v218, v0
	v_add_f32_e32 v196, v203, v204
	v_add_f32_e32 v196, v205, v196
	v_add_f32_e32 v196, v206, v196
	v_add_f32_e32 v196, v207, v196
	v_add_f32_e32 v196, v208, v196
	v_add_f32_e32 v196, v209, v196
	v_add_f32_e32 v196, v210, v196
	v_add_f32_e32 v196, v211, v196
	v_add_f32_e32 v196, v212, v196
	v_add_f32_e32 v196, v213, v196
	v_add_f32_e32 v196, v214, v196
	v_add_f32_e32 v196, v215, v196
	v_add_f32_e32 v196, v216, v196
	v_add_f32_e32 v196, v217, v196
	v_add_f32_e32 v196, v218, v196
	s_branch .Lwin_join0
.Lwin_slow1:
	v_max_f32_e32 v181, v66, v67
	v_max3_f32 v181, v181, v68, v69
	v_max3_f32 v181, v181, v70, v71
	v_max3_f32 v181, v181, v72, v73
	v_max3_f32 v181, v181, v74, v75
	v_max3_f32 v181, v181, v76, v77
	v_max3_f32 v181, v181, v78, v79
	v_max3_f32 v181, v181, v80, v81
	v_mov_b32_e32 v182, v181
	s_nop 1
	v_permlane32_swap_b32_e32 v181, v182
	v_max_f32_e32 v181, v181, v182
	v_mul_f32_e32 v181, 0x3e38aa3b, v181
	v_max_f32_e32 v181, v180, v181
	v_sub_f32_e32 v182, v181, v180
	v_cmp_lt_f32_e32 vcc, s67, v182
	s_cbranch_vccz .Lwin_slow1_nr
	v_sub_f32_e32 v182, v180, v181
	v_exp_f32_e32 v204, v182
	s_nop 0
	v_mul_f32_e32 v146, v146, v204
	v_pk_mul_f32 v[32:33], v[32:33], v[204:205] op_sel_hi:[1,0]
	v_pk_mul_f32 v[30:31], v[30:31], v[204:205] op_sel_hi:[1,0]
	v_pk_mul_f32 v[28:29], v[28:29], v[204:205] op_sel_hi:[1,0]
	v_pk_mul_f32 v[26:27], v[26:27], v[204:205] op_sel_hi:[1,0]
	v_pk_mul_f32 v[24:25], v[24:25], v[204:205] op_sel_hi:[1,0]
	v_pk_mul_f32 v[22:23], v[22:23], v[204:205] op_sel_hi:[1,0]
	v_pk_mul_f32 v[20:21], v[20:21], v[204:205] op_sel_hi:[1,0]
	v_pk_mul_f32 v[18:19], v[18:19], v[204:205] op_sel_hi:[1,0]
	v_pk_mul_f32 v[16:17], v[16:17], v[204:205] op_sel_hi:[1,0]
	v_pk_mul_f32 v[14:15], v[14:15], v[204:205] op_sel_hi:[1,0]
	v_pk_mul_f32 v[12:13], v[12:13], v[204:205] op_sel_hi:[1,0]
	v_pk_mul_f32 v[10:11], v[10:11], v[204:205] op_sel_hi:[1,0]
	v_pk_mul_f32 v[8:9], v[8:9], v[204:205] op_sel_hi:[1,0]
	v_pk_mul_f32 v[6:7], v[6:7], v[204:205] op_sel_hi:[1,0]
	v_pk_mul_f32 v[4:5], v[4:5], v[204:205] op_sel_hi:[1,0]
	v_pk_mul_f32 v[2:3], v[2:3], v[204:205] op_sel_hi:[1,0]
	v_mov_b32_e32 v180, v181
.Lwin_slow1_nr:
	v_fma_f32 v181, v66, s66, -v180
	v_exp_f32_e32 v203, v181
	v_fma_f32 v181, v67, s66, -v180
	v_exp_f32_e32 v204, v181
	v_fma_f32 v181, v68, s66, -v180
	v_exp_f32_e32 v205, v181
	v_fma_f32 v181, v69, s66, -v180
	v_exp_f32_e32 v206, v181
	v_fma_f32 v181, v70, s66, -v180
	v_exp_f32_e32 v207, v181
	v_fma_f32 v181, v71, s66, -v180
	v_exp_f32_e32 v208, v181
	v_fma_f32 v181, v72, s66, -v180
	v_exp_f32_e32 v209, v181
	v_fma_f32 v181, v73, s66, -v180
	v_exp_f32_e32 v210, v181
	v_fma_f32 v181, v74, s66, -v180
	v_exp_f32_e32 v211, v181
	v_fma_f32 v181, v75, s66, -v180
	v_exp_f32_e32 v212, v181
	v_fma_f32 v181, v76, s66, -v180
	v_exp_f32_e32 v213, v181
	v_fma_f32 v181, v77, s66, -v180
	v_exp_f32_e32 v214, v181
	v_fma_f32 v181, v78, s66, -v180
	v_exp_f32_e32 v215, v181
	v_fma_f32 v181, v79, s66, -v180
	v_exp_f32_e32 v216, v181
	v_fma_f32 v181, v80, s66, -v180
	v_exp_f32_e32 v217, v181
	v_fma_f32 v181, v81, s66, -v180
	v_exp_f32_e32 v218, v181
	v_add_f32_e32 v182, v203, v204
	v_add_f32_e32 v182, v205, v182
	v_add_f32_e32 v182, v206, v182
	v_add_f32_e32 v182, v207, v182
	v_add_f32_e32 v182, v208, v182
	v_add_f32_e32 v182, v209, v182
	v_add_f32_e32 v182, v210, v182
	v_add_f32_e32 v182, v211, v182
	v_add_f32_e32 v182, v212, v182
	v_add_f32_e32 v182, v213, v182
	v_add_f32_e32 v182, v214, v182
	v_add_f32_e32 v182, v215, v182
	v_add_f32_e32 v182, v216, v182
	v_add_f32_e32 v182, v217, v182
	v_add_f32_e32 v182, v218, v182
	s_branch .Lwin_join1
